# attention finalize (MODE 0/1/2 copies): the 8 serialized z-gate loads per item are issued together and per-group waits dropped
# baseline (speedup 1.0000x reference)
; DI uint32_t pack2(float a, float b) { f2_t v = {a, b}; bf2_t r = __builtin_convertvector(v, bf2_t); return __builtin_bit_cast(uint32_t, r); }
; DI float bflo(uint32_t u) { return __uint_as_float(u << 16); }
; DI float bfhi(uint32_t u) { return __uint_as_float(u & 0xffff0000u); }
; DI float xsum32(float v) { unsigned u = __float_as_uint(v); auto r = __builtin_amdgcn_permlane32_swap(u, u, false, false); return __uint_as_float(r[0]) + __uint_as_float(r[1]); }
; DI float fsigmoid(float x) { return frcp(1.f + fexp2(-LOG2E * x)); }
; template <int MODE, bool FAST>
; DI void attn_item(const Params& p, int layer, int b, int hd, int qt, char* smem) {
;     ...
;   float inv = 1.f;
;   if (MODE != 0) { const float lt = xsum32(lrun); inv = 1.f / lt; }
;   const size_t tok = (size_t)(tokbase + tq);
;   const u16* zrow = PROJ + tok * LDP + O_ZA + MODE * 512 + hdl * 64;
;   u16* yrow = YBR + tok * LDY + MODE * 512 + hdl * 64;
; #pragma unroll
;   for (int dt = 0; dt < 2; ++dt)
; #pragma unroll
;     for (int g = 0; g < 4; ++g) {
;       const int d4 = dt * 32 + 8 * g + 4 * h;
;       uint2 zu = *(const uint2*)(zrow + d4);
;       float z0 = bflo(zu.x), z1 = bfhi(zu.x), z2 = bflo(zu.y), z3 = bfhi(zu.y);
;       float y0 = o[dt][4 * g] * inv, y1 = o[dt][4 * g + 1] * inv, y2 = o[dt][4 * g + 2] * inv, y3 = o[dt][4 * g + 3] * inv;
;       y0 *= z0 * fsigmoid(z0); y1 *= z1 * fsigmoid(z1); y2 *= z2 * fsigmoid(z2); y3 *= z3 * fsigmoid(z3);
;       *(uint2*)(yrow + d4) = make_uint2(pack2(y0, y1), pack2(y2, y3));
;     }
.LBB0_99:
	v_mov_b32_e32 v0, v117
	s_nop 1
	v_permlane32_swap_b32_e32 v117, v0
	v_add_f32_e32 v0, v117, v0
	v_div_scale_f32 v1, s[40:41], v0, v0, 1.0
	v_rcp_f32_e32 v2, v1
	s_lshl_b32 s16, s7, 7
	s_movk_i32 s6, 0xdd80
	v_mov_b32_e32 v51, v3
	v_fma_f32 v4, -v1, v2, 1.0
	v_fmac_f32_e32 v2, v4, v2
	v_div_scale_f32 v4, vcc, 1.0, v0, 1.0
	v_mul_f32_e32 v5, v4, v2
	v_fma_f32 v6, -v1, v5, v4
	v_fmac_f32_e32 v5, v6, v2
	v_fma_f32 v1, -v1, v5, v4
	v_div_fmas_f32 v1, v1, v2, v5
	v_div_fixup_f32 v0, v1, v0, 1.0
	v_lshl_add_u32 v1, s58, 12, v110
	v_mov_b64_e32 v[4:5], s[94:95]
	v_mad_i64_i32 v[4:5], s[40:41], v1, s54, v[4:5]
	v_lshl_add_u64 v[6:7], v[4:5], 0, s[16:17]
	v_mad_i64_i32 v[4:5], s[40:41], v1, s6, v[4:5]
	v_lshlrev_b64 v[8:9], 1, v[50:51]
	v_lshl_add_u64 v[10:11], v[6:7], 0, v[8:9]
	s_mov_b64 s[40:41], 0x4e98e80
	s_mov_b32 s6, 0x4e98000
	v_lshl_add_u64 v[6:7], v[10:11], 0, s[40:41]
	v_add_co_u32_e32 v10, vcc, s6, v10
	v_pk_mul_f32 v[14:15], v[34:35], v[0:1] op_sel_hi:[1,0]
	s_nop 0
	v_addc_co_u32_e32 v11, vcc, 0, v11, vcc
	global_load_dwordx2 v[10:11], v[10:11], off offset:3712
	global_load_dwordx2 v[96:97], v[6:7], off offset:16
	global_load_dwordx2 v[98:99], v[6:7], off offset:32
	global_load_dwordx2 v[100:101], v[6:7], off offset:48
	global_load_dwordx2 v[102:103], v[6:7], off offset:64
	global_load_dwordx2 v[104:105], v[6:7], off offset:80
	global_load_dwordx2 v[106:107], v[6:7], off offset:96
	global_load_dwordx2 v[108:109], v[6:7], off offset:112
	v_lshl_add_u64 v[4:5], v[4:5], 0, s[16:17]
	v_lshl_add_u64 v[8:9], v[4:5], 0, v[8:9]
	s_mov_b64 s[40:41], 0x15c98400
	v_lshl_add_u64 v[4:5], v[8:9], 0, s[40:41]
	v_add_co_u32_e32 v8, vcc, s3, v8
	s_mov_b64 s[40:41], 0x70
	s_nop 0
	v_addc_co_u32_e32 v9, vcc, 0, v9, vcc
	s_waitcnt vmcnt(0)
	v_lshlrev_b32_e32 v12, 16, v10
	v_mul_f32_e32 v1, 0xbfb8aa3b, v12
	v_exp_f32_e32 v1, v1
	v_and_b32_e32 v13, 0xffff0000, v10
	v_lshlrev_b32_e32 v10, 16, v11
	v_and_b32_e32 v11, 0xffff0000, v11
	v_add_f32_e32 v1, 1.0, v1
	v_rcp_f32_e32 v16, v1
	v_mul_f32_e32 v1, 0xbfb8aa3b, v13
	v_exp_f32_e32 v1, v1
	s_nop 0
	v_add_f32_e32 v1, 1.0, v1
	v_rcp_f32_e32 v17, v1
	s_nop 0
	v_pk_mul_f32 v[12:13], v[16:17], v[12:13]
	s_nop 0
	v_pk_mul_f32 v[12:13], v[14:15], v[12:13]
	v_pk_mul_f32 v[14:15], v[36:37], v[0:1] op_sel_hi:[1,0]
	v_mul_f32_e32 v1, 0xbfb8aa3b, v10
	v_exp_f32_e32 v1, v1
	v_cvt_pk_bf16_f32 v12, v12, v13
	v_add_f32_e32 v1, 1.0, v1
	v_rcp_f32_e32 v16, v1
	v_mul_f32_e32 v1, 0xbfb8aa3b, v11
	v_exp_f32_e32 v1, v1
	s_nop 0
	v_add_f32_e32 v1, 1.0, v1
	v_rcp_f32_e32 v17, v1
	s_nop 0
	v_pk_mul_f32 v[10:11], v[16:17], v[10:11]
	s_nop 0
	v_pk_mul_f32 v[10:11], v[14:15], v[10:11]
	s_nop 0
	v_cvt_pk_bf16_f32 v13, v10, v11
	global_store_dwordx2 v[8:9], v[12:13], off offset:1024
	v_mov_b64_e32 v[8:9], v[96:97]
	v_pk_mul_f32 v[12:13], v[38:39], v[0:1] op_sel_hi:[1,0]
	v_lshlrev_b32_e32 v10, 16, v8
	v_mul_f32_e32 v1, 0xbfb8aa3b, v10
	v_exp_f32_e32 v1, v1
	v_and_b32_e32 v11, 0xffff0000, v8
	v_lshlrev_b32_e32 v8, 16, v9
	v_and_b32_e32 v9, 0xffff0000, v9
	v_add_f32_e32 v1, 1.0, v1
	v_rcp_f32_e32 v14, v1
	v_mul_f32_e32 v1, 0xbfb8aa3b, v11
	v_exp_f32_e32 v1, v1
	s_nop 0
	v_add_f32_e32 v1, 1.0, v1
	v_rcp_f32_e32 v15, v1
	s_nop 0
	v_pk_mul_f32 v[10:11], v[14:15], v[10:11]
	s_nop 0
	v_pk_mul_f32 v[10:11], v[12:13], v[10:11]
	v_pk_mul_f32 v[12:13], v[40:41], v[0:1] op_sel_hi:[1,0]
	v_mul_f32_e32 v1, 0xbfb8aa3b, v8
	v_exp_f32_e32 v1, v1
	v_cvt_pk_bf16_f32 v10, v10, v11
	v_add_f32_e32 v1, 1.0, v1
	v_rcp_f32_e32 v14, v1
	v_mul_f32_e32 v1, 0xbfb8aa3b, v9
	v_exp_f32_e32 v1, v1
	s_nop 0
	v_add_f32_e32 v1, 1.0, v1
	v_rcp_f32_e32 v15, v1
	s_nop 0
	v_pk_mul_f32 v[8:9], v[14:15], v[8:9]
	s_nop 0
	v_pk_mul_f32 v[8:9], v[12:13], v[8:9]
	v_pk_mul_f32 v[12:13], v[42:43], v[0:1] op_sel_hi:[1,0]
	v_cvt_pk_bf16_f32 v11, v8, v9
	v_mov_b64_e32 v[8:9], v[98:99]
	s_nop 0
	global_store_dwordx2 v[4:5], v[10:11], off offset:16
	v_lshlrev_b32_e32 v10, 16, v8
	v_mul_f32_e32 v1, 0xbfb8aa3b, v10
	v_exp_f32_e32 v1, v1
	v_and_b32_e32 v11, 0xffff0000, v8
	v_lshlrev_b32_e32 v8, 16, v9
	v_and_b32_e32 v9, 0xffff0000, v9
	v_add_f32_e32 v1, 1.0, v1
	v_rcp_f32_e32 v14, v1
	v_mul_f32_e32 v1, 0xbfb8aa3b, v11
	v_exp_f32_e32 v1, v1
	s_nop 0
	v_add_f32_e32 v1, 1.0, v1
	v_rcp_f32_e32 v15, v1
	s_nop 0
	v_pk_mul_f32 v[10:11], v[14:15], v[10:11]
	s_nop 0
	v_pk_mul_f32 v[10:11], v[12:13], v[10:11]
	v_pk_mul_f32 v[12:13], v[44:45], v[0:1] op_sel_hi:[1,0]
	v_mul_f32_e32 v1, 0xbfb8aa3b, v8
	v_exp_f32_e32 v1, v1
	v_cvt_pk_bf16_f32 v10, v10, v11
	v_add_f32_e32 v1, 1.0, v1
	v_rcp_f32_e32 v14, v1
	v_mul_f32_e32 v1, 0xbfb8aa3b, v9
	v_exp_f32_e32 v1, v1
	s_nop 0
	v_add_f32_e32 v1, 1.0, v1
	v_rcp_f32_e32 v15, v1
	s_nop 0
	v_pk_mul_f32 v[8:9], v[14:15], v[8:9]
	s_nop 0
	v_pk_mul_f32 v[8:9], v[12:13], v[8:9]
	v_pk_mul_f32 v[12:13], v[46:47], v[0:1] op_sel_hi:[1,0]
	v_cvt_pk_bf16_f32 v11, v8, v9
	v_mov_b64_e32 v[8:9], v[100:101]
	s_nop 0
	global_store_dwordx2 v[4:5], v[10:11], off offset:32
	v_lshlrev_b32_e32 v10, 16, v8
	v_mul_f32_e32 v1, 0xbfb8aa3b, v10
	v_exp_f32_e32 v1, v1
	v_and_b32_e32 v11, 0xffff0000, v8
; DI uint32_t pack2(float a, float b) { f2_t v = {a, b}; bf2_t r = __builtin_convertvector(v, bf2_t); return __builtin_bit_cast(uint32_t, r); }
; DI float bflo(uint32_t u) { return __uint_as_float(u << 16); }
; DI float bfhi(uint32_t u) { return __uint_as_float(u & 0xffff0000u); }
; DI float fsigmoid(float x) { return frcp(1.f + fexp2(-LOG2E * x)); }
; template <int MODE, bool FAST>
; DI void attn_item(const Params& p, int layer, int b, int hd, int qt, char* smem) {
;     ...
;       const int d4 = dt * 32 + 8 * g + 4 * h;
;       uint2 zu = *(const uint2*)(zrow + d4);
;       float z0 = bflo(zu.x), z1 = bfhi(zu.x), z2 = bflo(zu.y), z3 = bfhi(zu.y);
;       float y0 = o[dt][4 * g] * inv, y1 = o[dt][4 * g + 1] * inv, y2 = o[dt][4 * g + 2] * inv, y3 = o[dt][4 * g + 3] * inv;
;       y0 *= z0 * fsigmoid(z0); y1 *= z1 * fsigmoid(z1); y2 *= z2 * fsigmoid(z2); y3 *= z3 * fsigmoid(z3);
;       *(uint2*)(yrow + d4) = make_uint2(pack2(y0, y1), pack2(y2, y3));
;     }
	v_lshlrev_b32_e32 v8, 16, v9
	v_and_b32_e32 v9, 0xffff0000, v9
	v_add_f32_e32 v1, 1.0, v1
	v_rcp_f32_e32 v14, v1
	v_mul_f32_e32 v1, 0xbfb8aa3b, v11
	v_exp_f32_e32 v1, v1
	s_nop 0
	v_add_f32_e32 v1, 1.0, v1
	v_rcp_f32_e32 v15, v1
	s_nop 0
	v_pk_mul_f32 v[10:11], v[14:15], v[10:11]
	s_nop 0
	v_pk_mul_f32 v[10:11], v[12:13], v[10:11]
	v_pk_mul_f32 v[12:13], v[48:49], v[0:1] op_sel_hi:[1,0]
	v_mul_f32_e32 v1, 0xbfb8aa3b, v8
	v_exp_f32_e32 v1, v1
	v_cvt_pk_bf16_f32 v10, v10, v11
	v_add_f32_e32 v1, 1.0, v1
	v_rcp_f32_e32 v14, v1
	v_mul_f32_e32 v1, 0xbfb8aa3b, v9
	v_exp_f32_e32 v1, v1
	s_nop 0
	v_add_f32_e32 v1, 1.0, v1
	v_rcp_f32_e32 v15, v1
	s_nop 0
	v_pk_mul_f32 v[8:9], v[14:15], v[8:9]
	s_nop 0
	v_pk_mul_f32 v[8:9], v[12:13], v[8:9]
	v_pk_mul_f32 v[12:13], v[18:19], v[0:1] op_sel_hi:[1,0]
	v_cvt_pk_bf16_f32 v11, v8, v9
	v_mov_b64_e32 v[8:9], v[102:103]
	s_nop 0
	global_store_dwordx2 v[4:5], v[10:11], off offset:48
	v_lshlrev_b32_e32 v10, 16, v8
	v_mul_f32_e32 v1, 0xbfb8aa3b, v10
	v_exp_f32_e32 v1, v1
	v_and_b32_e32 v11, 0xffff0000, v8
	v_lshlrev_b32_e32 v8, 16, v9
	v_and_b32_e32 v9, 0xffff0000, v9
	v_add_f32_e32 v1, 1.0, v1
	v_rcp_f32_e32 v14, v1
	v_mul_f32_e32 v1, 0xbfb8aa3b, v11
	v_exp_f32_e32 v1, v1
	s_nop 0
	v_add_f32_e32 v1, 1.0, v1
	v_rcp_f32_e32 v15, v1
	s_nop 0
	v_pk_mul_f32 v[10:11], v[14:15], v[10:11]
	s_nop 0
	v_pk_mul_f32 v[10:11], v[12:13], v[10:11]
	v_pk_mul_f32 v[12:13], v[20:21], v[0:1] op_sel_hi:[1,0]
	v_mul_f32_e32 v1, 0xbfb8aa3b, v8
	v_exp_f32_e32 v1, v1
	v_cvt_pk_bf16_f32 v10, v10, v11
	v_add_f32_e32 v1, 1.0, v1
	v_rcp_f32_e32 v14, v1
	v_mul_f32_e32 v1, 0xbfb8aa3b, v9
	v_exp_f32_e32 v1, v1
	s_nop 0
	v_add_f32_e32 v1, 1.0, v1
	v_rcp_f32_e32 v15, v1
	s_nop 0
	v_pk_mul_f32 v[8:9], v[14:15], v[8:9]
	s_nop 0
	v_pk_mul_f32 v[8:9], v[12:13], v[8:9]
	v_pk_mul_f32 v[12:13], v[22:23], v[0:1] op_sel_hi:[1,0]
	v_cvt_pk_bf16_f32 v11, v8, v9
	v_mov_b64_e32 v[8:9], v[104:105]
	s_nop 0
	global_store_dwordx2 v[4:5], v[10:11], off offset:64
	v_lshlrev_b32_e32 v10, 16, v8
	v_mul_f32_e32 v1, 0xbfb8aa3b, v10
	v_exp_f32_e32 v1, v1
	v_and_b32_e32 v11, 0xffff0000, v8
	v_lshlrev_b32_e32 v8, 16, v9
	v_and_b32_e32 v9, 0xffff0000, v9
	v_add_f32_e32 v1, 1.0, v1
	v_rcp_f32_e32 v14, v1
	v_mul_f32_e32 v1, 0xbfb8aa3b, v11
	v_exp_f32_e32 v1, v1
	s_nop 0
	v_add_f32_e32 v1, 1.0, v1
	v_rcp_f32_e32 v15, v1
	s_nop 0
	v_pk_mul_f32 v[10:11], v[14:15], v[10:11]
	s_nop 0
	v_pk_mul_f32 v[10:11], v[12:13], v[10:11]
	v_pk_mul_f32 v[12:13], v[24:25], v[0:1] op_sel_hi:[1,0]
	v_mul_f32_e32 v1, 0xbfb8aa3b, v8
	v_exp_f32_e32 v1, v1
	v_cvt_pk_bf16_f32 v10, v10, v11
	v_add_f32_e32 v1, 1.0, v1
	v_rcp_f32_e32 v14, v1
	v_mul_f32_e32 v1, 0xbfb8aa3b, v9
	v_exp_f32_e32 v1, v1
	s_nop 0
	v_add_f32_e32 v1, 1.0, v1
	v_rcp_f32_e32 v15, v1
	s_nop 0
	v_pk_mul_f32 v[8:9], v[14:15], v[8:9]
	s_nop 0
	v_pk_mul_f32 v[8:9], v[12:13], v[8:9]
	v_pk_mul_f32 v[12:13], v[26:27], v[0:1] op_sel_hi:[1,0]
	v_cvt_pk_bf16_f32 v11, v8, v9
	v_mov_b64_e32 v[8:9], v[106:107]
	s_nop 0
	v_mov_b64_e32 v[6:7], v[108:109]
	v_lshlrev_b32_e32 v2, 16, v7
	global_store_dwordx2 v[4:5], v[10:11], off offset:80
	v_lshlrev_b32_e32 v10, 16, v8
	v_mul_f32_e32 v1, 0xbfb8aa3b, v10
	v_exp_f32_e32 v1, v1
	v_and_b32_e32 v11, 0xffff0000, v8
	v_lshlrev_b32_e32 v8, 16, v9
	v_and_b32_e32 v9, 0xffff0000, v9
	v_add_f32_e32 v1, 1.0, v1
	v_rcp_f32_e32 v14, v1
	v_mul_f32_e32 v1, 0xbfb8aa3b, v11
	v_exp_f32_e32 v1, v1
	s_nop 0
	v_add_f32_e32 v1, 1.0, v1
	v_rcp_f32_e32 v15, v1
	s_nop 0
	v_pk_mul_f32 v[10:11], v[14:15], v[10:11]
	s_nop 0
	v_pk_mul_f32 v[10:11], v[12:13], v[10:11]
	v_pk_mul_f32 v[12:13], v[28:29], v[0:1] op_sel_hi:[1,0]
	v_mul_f32_e32 v1, 0xbfb8aa3b, v8
	v_exp_f32_e32 v1, v1
	v_cvt_pk_bf16_f32 v10, v10, v11
	v_add_f32_e32 v1, 1.0, v1
	v_rcp_f32_e32 v14, v1
	v_mul_f32_e32 v1, 0xbfb8aa3b, v9
	v_exp_f32_e32 v1, v1
	s_nop 0
	v_add_f32_e32 v1, 1.0, v1
	v_rcp_f32_e32 v15, v1
	v_and_b32_e32 v1, 0xffff0000, v7
	v_pk_mul_f32 v[8:9], v[14:15], v[8:9]
	s_nop 0
	v_pk_mul_f32 v[8:9], v[12:13], v[8:9]
	s_nop 0
	v_cvt_pk_bf16_f32 v11, v8, v9
	v_lshlrev_b32_e32 v8, 16, v6
	v_mul_f32_e32 v7, 0xbfb8aa3b, v8
	v_exp_f32_e32 v7, v7
	v_and_b32_e32 v9, 0xffff0000, v6
	global_store_dwordx2 v[4:5], v[10:11], off offset:96
	v_pk_mul_f32 v[10:11], v[30:31], v[0:1] op_sel_hi:[1,0]
	v_add_f32_e32 v7, 1.0, v7
	v_rcp_f32_e32 v12, v7
	v_mul_f32_e32 v7, 0xbfb8aa3b, v9
	v_exp_f32_e32 v7, v7
	v_mul_f32_e32 v6, v32, v0
	v_add_f32_e32 v7, 1.0, v7
	v_rcp_f32_e32 v13, v7
	v_mul_f32_e32 v7, 0xbfb8aa3b, v2
	v_exp_f32_e32 v7, v7
	v_pk_mul_f32 v[8:9], v[12:13], v[8:9]
	s_nop 0
	v_pk_mul_f32 v[8:9], v[10:11], v[8:9]
	v_add_f32_e32 v7, 1.0, v7
	v_rcp_f32_e32 v7, v7
	v_mov_b32_e32 v12, v33
	v_mul_f32_e32 v10, v7, v2
	v_mul_f32_e32 v2, 0xbfb8aa3b, v1
	v_exp_f32_e32 v2, v2
	s_nop 0
	v_add_f32_e32 v2, 1.0, v2
	v_rcp_f32_e32 v13, v2
	s_nop 0
	v_pk_mul_f32 v[0:1], v[12:13], v[0:1]
	s_nop 0
	v_mov_b32_e32 v7, v0
	v_mov_b32_e32 v11, v1
	v_cvt_pk_bf16_f32 v0, v8, v9
	v_pk_mul_f32 v[6:7], v[6:7], v[10:11]
	v_lshl_add_u64 v[8:9], v[4:5], 0, s[40:41]
	global_store_dword v[4:5], v0, off offset:112
	s_mov_b64 s[40:41], 0

; DI uint32_t pack2(float a, float b) { f2_t v = {a, b}; bf2_t r = __builtin_convertvector(v, bf2_t); return __builtin_bit_cast(uint32_t, r); }
; DI float bflo(uint32_t u) { return __uint_as_float(u << 16); }
; DI float bfhi(uint32_t u) { return __uint_as_float(u & 0xffff0000u); }
; DI float xsum32(float v) { unsigned u = __float_as_uint(v); auto r = __builtin_amdgcn_permlane32_swap(u, u, false, false); return __uint_as_float(r[0]) + __uint_as_float(r[1]); }
; DI float fsigmoid(float x) { return frcp(1.f + fexp2(-LOG2E * x)); }
; template <int MODE, bool FAST>
; DI void attn_item(const Params& p, int layer, int b, int hd, int qt, char* smem) {
;     ...
;   float inv = 1.f;
;   if (MODE != 0) { const float lt = xsum32(lrun); inv = 1.f / lt; }
;   const size_t tok = (size_t)(tokbase + tq);
;   const u16* zrow = PROJ + tok * LDP + O_ZA + MODE * 512 + hdl * 64;
;   u16* yrow = YBR + tok * LDY + MODE * 512 + hdl * 64;
; #pragma unroll
;   for (int dt = 0; dt < 2; ++dt)
; #pragma unroll
;     for (int g = 0; g < 4; ++g) {
;       const int d4 = dt * 32 + 8 * g + 4 * h;
;       uint2 zu = *(const uint2*)(zrow + d4);
;       float z0 = bflo(zu.x), z1 = bfhi(zu.x), z2 = bflo(zu.y), z3 = bfhi(zu.y);
;       float y0 = o[dt][4 * g] * inv, y1 = o[dt][4 * g + 1] * inv, y2 = o[dt][4 * g + 2] * inv, y3 = o[dt][4 * g + 3] * inv;
;       y0 *= z0 * fsigmoid(z0); y1 *= z1 * fsigmoid(z1); y2 *= z2 * fsigmoid(z2); y3 *= z3 * fsigmoid(z3);
;       *(uint2*)(yrow + d4) = make_uint2(pack2(y0, y1), pack2(y2, y3));
;     }
.LBB0_276:
	v_mov_b32_e32 v0, v165
	s_nop 1
	v_permlane32_swap_b32_e32 v165, v0
	v_add_f32_e32 v0, v165, v0
	v_div_scale_f32 v2, s[12:13], v0, v0, 1.0
	v_rcp_f32_e32 v4, v2
	v_lshlrev_b32_e32 v1, 6, v169
	s_movk_i32 s54, 0x2f00
	s_movk_i32 s5, 0xdd80
	v_fma_f32 v5, -v2, v4, 1.0
	v_fmac_f32_e32 v4, v5, v4
	v_div_scale_f32 v5, vcc, 1.0, v0, 1.0
	v_mul_f32_e32 v6, v5, v4
	v_fma_f32 v7, -v2, v6, v5
	v_fmac_f32_e32 v6, v7, v4
	v_fma_f32 v2, -v2, v6, v5
	v_div_fmas_f32 v2, v2, v4, v6
	v_mov_b64_e32 v[4:5], s[94:95]
	v_div_fixup_f32 v0, v2, v0, 1.0
	v_mad_i64_i32 v[4:5], s[12:13], v150, s54, v[4:5]
	v_lshlrev_b32_e32 v2, 1, v1
	v_mov_b32_e32 v169, v3
	v_lshl_add_u64 v[6:7], v[4:5], 0, v[2:3]
	v_mad_i64_i32 v[4:5], s[12:13], v150, s5, v[4:5]
	v_lshlrev_b64 v[8:9], 1, v[168:169]
	v_lshl_add_u64 v[10:11], v[6:7], 0, v[8:9]
	s_mov_b64 s[12:13], 0x4e99280
	s_mov_b32 s5, 0x4e99000
	v_lshl_add_u64 v[6:7], v[10:11], 0, s[12:13]
	v_add_co_u32_e32 v10, vcc, s5, v10
	v_pk_mul_f32 v[14:15], v[34:35], v[0:1] op_sel_hi:[1,0]
	s_nop 0
	v_addc_co_u32_e32 v11, vcc, 0, v11, vcc
	global_load_dwordx2 v[10:11], v[10:11], off offset:640
	global_load_dwordx2 v[96:97], v[6:7], off offset:16
	global_load_dwordx2 v[98:99], v[6:7], off offset:32
	global_load_dwordx2 v[100:101], v[6:7], off offset:48
	global_load_dwordx2 v[102:103], v[6:7], off offset:64
	global_load_dwordx2 v[104:105], v[6:7], off offset:80
	global_load_dwordx2 v[106:107], v[6:7], off offset:96
	global_load_dwordx2 v[108:109], v[6:7], off offset:112
	v_lshl_add_u64 v[4:5], v[4:5], 0, v[2:3]
	v_lshl_add_u64 v[8:9], v[4:5], 0, v[8:9]
	s_mov_b64 s[12:13], 0x15c98800
	v_lshl_add_u64 v[4:5], v[8:9], 0, s[12:13]
	v_add_co_u32_e32 v8, vcc, s3, v8
	s_mov_b64 s[12:13], 0x70
	s_nop 0
	v_addc_co_u32_e32 v9, vcc, 0, v9, vcc
	s_waitcnt vmcnt(0)
	v_lshlrev_b32_e32 v12, 16, v10
	v_mul_f32_e32 v1, 0xbfb8aa3b, v12
	v_exp_f32_e32 v1, v1
	v_and_b32_e32 v13, 0xffff0000, v10
	v_lshlrev_b32_e32 v10, 16, v11
	v_and_b32_e32 v11, 0xffff0000, v11
	v_add_f32_e32 v1, 1.0, v1
	v_rcp_f32_e32 v16, v1
	v_mul_f32_e32 v1, 0xbfb8aa3b, v13
	v_exp_f32_e32 v1, v1
	s_nop 0
	v_add_f32_e32 v1, 1.0, v1
	v_rcp_f32_e32 v17, v1
	s_nop 0
	v_pk_mul_f32 v[12:13], v[16:17], v[12:13]
	s_nop 0
	v_pk_mul_f32 v[12:13], v[14:15], v[12:13]
	v_pk_mul_f32 v[14:15], v[36:37], v[0:1] op_sel_hi:[1,0]
	v_mul_f32_e32 v1, 0xbfb8aa3b, v10
	v_exp_f32_e32 v1, v1
	v_cvt_pk_bf16_f32 v12, v12, v13
	v_add_f32_e32 v1, 1.0, v1
	v_rcp_f32_e32 v16, v1
	v_mul_f32_e32 v1, 0xbfb8aa3b, v11
	v_exp_f32_e32 v1, v1
	s_nop 0
	v_add_f32_e32 v1, 1.0, v1
	v_rcp_f32_e32 v17, v1
	s_nop 0
	v_pk_mul_f32 v[10:11], v[16:17], v[10:11]
	s_nop 0
	v_pk_mul_f32 v[10:11], v[14:15], v[10:11]
	s_nop 0
	v_cvt_pk_bf16_f32 v13, v10, v11
	global_store_dwordx2 v[8:9], v[12:13], off offset:2048
	v_mov_b64_e32 v[8:9], v[96:97]
	v_pk_mul_f32 v[12:13], v[38:39], v[0:1] op_sel_hi:[1,0]
	v_lshlrev_b32_e32 v10, 16, v8
	v_mul_f32_e32 v1, 0xbfb8aa3b, v10
	v_exp_f32_e32 v1, v1
	v_and_b32_e32 v11, 0xffff0000, v8
	v_lshlrev_b32_e32 v8, 16, v9
	v_and_b32_e32 v9, 0xffff0000, v9
	v_add_f32_e32 v1, 1.0, v1
	v_rcp_f32_e32 v14, v1
	v_mul_f32_e32 v1, 0xbfb8aa3b, v11
	v_exp_f32_e32 v1, v1
	s_nop 0
	v_add_f32_e32 v1, 1.0, v1
	v_rcp_f32_e32 v15, v1
	s_nop 0
	v_pk_mul_f32 v[10:11], v[14:15], v[10:11]
	s_nop 0
	v_pk_mul_f32 v[10:11], v[12:13], v[10:11]
	v_pk_mul_f32 v[12:13], v[40:41], v[0:1] op_sel_hi:[1,0]
	v_mul_f32_e32 v1, 0xbfb8aa3b, v8
	v_exp_f32_e32 v1, v1
	v_cvt_pk_bf16_f32 v10, v10, v11
	v_add_f32_e32 v1, 1.0, v1
	v_rcp_f32_e32 v14, v1
	v_mul_f32_e32 v1, 0xbfb8aa3b, v9
	v_exp_f32_e32 v1, v1
	s_nop 0
	v_add_f32_e32 v1, 1.0, v1
	v_rcp_f32_e32 v15, v1
	s_nop 0
	v_pk_mul_f32 v[8:9], v[14:15], v[8:9]
	s_nop 0
	v_pk_mul_f32 v[8:9], v[12:13], v[8:9]
	v_pk_mul_f32 v[12:13], v[42:43], v[0:1] op_sel_hi:[1,0]
	v_cvt_pk_bf16_f32 v11, v8, v9
	v_mov_b64_e32 v[8:9], v[98:99]
	s_nop 0
	global_store_dwordx2 v[4:5], v[10:11], off offset:16
	v_lshlrev_b32_e32 v10, 16, v8
	v_mul_f32_e32 v1, 0xbfb8aa3b, v10
	v_exp_f32_e32 v1, v1
	v_and_b32_e32 v11, 0xffff0000, v8
	v_lshlrev_b32_e32 v8, 16, v9
	v_and_b32_e32 v9, 0xffff0000, v9
	v_add_f32_e32 v1, 1.0, v1
	v_rcp_f32_e32 v14, v1
	v_mul_f32_e32 v1, 0xbfb8aa3b, v11
	v_exp_f32_e32 v1, v1
	s_nop 0
	v_add_f32_e32 v1, 1.0, v1
	v_rcp_f32_e32 v15, v1
	s_nop 0
	v_pk_mul_f32 v[10:11], v[14:15], v[10:11]
	s_nop 0
	v_pk_mul_f32 v[10:11], v[12:13], v[10:11]
	v_pk_mul_f32 v[12:13], v[44:45], v[0:1] op_sel_hi:[1,0]
	v_mul_f32_e32 v1, 0xbfb8aa3b, v8
	v_exp_f32_e32 v1, v1
	v_cvt_pk_bf16_f32 v10, v10, v11
	v_add_f32_e32 v1, 1.0, v1
	v_rcp_f32_e32 v14, v1
	v_mul_f32_e32 v1, 0xbfb8aa3b, v9
	v_exp_f32_e32 v1, v1
	s_nop 0
	v_add_f32_e32 v1, 1.0, v1
	v_rcp_f32_e32 v15, v1
	s_nop 0
	v_pk_mul_f32 v[8:9], v[14:15], v[8:9]
	s_nop 0
	v_pk_mul_f32 v[8:9], v[12:13], v[8:9]
	v_pk_mul_f32 v[12:13], v[46:47], v[0:1] op_sel_hi:[1,0]
	v_cvt_pk_bf16_f32 v11, v8, v9
	v_mov_b64_e32 v[8:9], v[100:101]
	s_nop 0
	global_store_dwordx2 v[4:5], v[10:11], off offset:32
	v_lshlrev_b32_e32 v10, 16, v8
	v_mul_f32_e32 v1, 0xbfb8aa3b, v10
	v_exp_f32_e32 v1, v1
	v_and_b32_e32 v11, 0xffff0000, v8
; DI uint32_t pack2(float a, float b) { f2_t v = {a, b}; bf2_t r = __builtin_convertvector(v, bf2_t); return __builtin_bit_cast(uint32_t, r); }
; DI float bflo(uint32_t u) { return __uint_as_float(u << 16); }
; DI float bfhi(uint32_t u) { return __uint_as_float(u & 0xffff0000u); }
; DI float fsigmoid(float x) { return frcp(1.f + fexp2(-LOG2E * x)); }
; template <int MODE, bool FAST>
; DI void attn_item(const Params& p, int layer, int b, int hd, int qt, char* smem) {
;     ...
;       const int d4 = dt * 32 + 8 * g + 4 * h;
;       uint2 zu = *(const uint2*)(zrow + d4);
;       float z0 = bflo(zu.x), z1 = bfhi(zu.x), z2 = bflo(zu.y), z3 = bfhi(zu.y);
;       float y0 = o[dt][4 * g] * inv, y1 = o[dt][4 * g + 1] * inv, y2 = o[dt][4 * g + 2] * inv, y3 = o[dt][4 * g + 3] * inv;
;       y0 *= z0 * fsigmoid(z0); y1 *= z1 * fsigmoid(z1); y2 *= z2 * fsigmoid(z2); y3 *= z3 * fsigmoid(z3);
;       *(uint2*)(yrow + d4) = make_uint2(pack2(y0, y1), pack2(y2, y3));
;     }
	v_lshlrev_b32_e32 v8, 16, v9
	v_and_b32_e32 v9, 0xffff0000, v9
	v_add_f32_e32 v1, 1.0, v1
	v_rcp_f32_e32 v14, v1
	v_mul_f32_e32 v1, 0xbfb8aa3b, v11
	v_exp_f32_e32 v1, v1
	s_nop 0
	v_add_f32_e32 v1, 1.0, v1
	v_rcp_f32_e32 v15, v1
	s_nop 0
	v_pk_mul_f32 v[10:11], v[14:15], v[10:11]
	s_nop 0
	v_pk_mul_f32 v[10:11], v[12:13], v[10:11]
	v_pk_mul_f32 v[12:13], v[48:49], v[0:1] op_sel_hi:[1,0]
	v_mul_f32_e32 v1, 0xbfb8aa3b, v8
	v_exp_f32_e32 v1, v1
	v_cvt_pk_bf16_f32 v10, v10, v11
	v_add_f32_e32 v1, 1.0, v1
	v_rcp_f32_e32 v14, v1
	v_mul_f32_e32 v1, 0xbfb8aa3b, v9
	v_exp_f32_e32 v1, v1
	s_nop 0
	v_add_f32_e32 v1, 1.0, v1
	v_rcp_f32_e32 v15, v1
	s_nop 0
	v_pk_mul_f32 v[8:9], v[14:15], v[8:9]
	s_nop 0
	v_pk_mul_f32 v[8:9], v[12:13], v[8:9]
	v_pk_mul_f32 v[12:13], v[18:19], v[0:1] op_sel_hi:[1,0]
	v_cvt_pk_bf16_f32 v11, v8, v9
	v_mov_b64_e32 v[8:9], v[102:103]
	s_nop 0
	global_store_dwordx2 v[4:5], v[10:11], off offset:48
	v_lshlrev_b32_e32 v10, 16, v8
	v_mul_f32_e32 v1, 0xbfb8aa3b, v10
	v_exp_f32_e32 v1, v1
	v_and_b32_e32 v11, 0xffff0000, v8
	v_lshlrev_b32_e32 v8, 16, v9
	v_and_b32_e32 v9, 0xffff0000, v9
	v_add_f32_e32 v1, 1.0, v1
	v_rcp_f32_e32 v14, v1
	v_mul_f32_e32 v1, 0xbfb8aa3b, v11
	v_exp_f32_e32 v1, v1
	s_nop 0
	v_add_f32_e32 v1, 1.0, v1
	v_rcp_f32_e32 v15, v1
	s_nop 0
	v_pk_mul_f32 v[10:11], v[14:15], v[10:11]
	s_nop 0
	v_pk_mul_f32 v[10:11], v[12:13], v[10:11]
	v_pk_mul_f32 v[12:13], v[20:21], v[0:1] op_sel_hi:[1,0]
	v_mul_f32_e32 v1, 0xbfb8aa3b, v8
	v_exp_f32_e32 v1, v1
	v_cvt_pk_bf16_f32 v10, v10, v11
	v_add_f32_e32 v1, 1.0, v1
	v_rcp_f32_e32 v14, v1
	v_mul_f32_e32 v1, 0xbfb8aa3b, v9
	v_exp_f32_e32 v1, v1
	s_nop 0
	v_add_f32_e32 v1, 1.0, v1
	v_rcp_f32_e32 v15, v1
	s_nop 0
	v_pk_mul_f32 v[8:9], v[14:15], v[8:9]
	s_nop 0
	v_pk_mul_f32 v[8:9], v[12:13], v[8:9]
	v_pk_mul_f32 v[12:13], v[22:23], v[0:1] op_sel_hi:[1,0]
	v_cvt_pk_bf16_f32 v11, v8, v9
	v_mov_b64_e32 v[8:9], v[104:105]
	s_nop 0
	global_store_dwordx2 v[4:5], v[10:11], off offset:64
	v_lshlrev_b32_e32 v10, 16, v8
	v_mul_f32_e32 v1, 0xbfb8aa3b, v10
	v_exp_f32_e32 v1, v1
	v_and_b32_e32 v11, 0xffff0000, v8
	v_lshlrev_b32_e32 v8, 16, v9
	v_and_b32_e32 v9, 0xffff0000, v9
	v_add_f32_e32 v1, 1.0, v1
	v_rcp_f32_e32 v14, v1
	v_mul_f32_e32 v1, 0xbfb8aa3b, v11
	v_exp_f32_e32 v1, v1
	s_nop 0
	v_add_f32_e32 v1, 1.0, v1
	v_rcp_f32_e32 v15, v1
	s_nop 0
	v_pk_mul_f32 v[10:11], v[14:15], v[10:11]
	s_nop 0
	v_pk_mul_f32 v[10:11], v[12:13], v[10:11]
	v_pk_mul_f32 v[12:13], v[24:25], v[0:1] op_sel_hi:[1,0]
	v_mul_f32_e32 v1, 0xbfb8aa3b, v8
	v_exp_f32_e32 v1, v1
	v_cvt_pk_bf16_f32 v10, v10, v11
	v_add_f32_e32 v1, 1.0, v1
	v_rcp_f32_e32 v14, v1
	v_mul_f32_e32 v1, 0xbfb8aa3b, v9
	v_exp_f32_e32 v1, v1
	s_nop 0
	v_add_f32_e32 v1, 1.0, v1
	v_rcp_f32_e32 v15, v1
	s_nop 0
	v_pk_mul_f32 v[8:9], v[14:15], v[8:9]
	s_nop 0
	v_pk_mul_f32 v[8:9], v[12:13], v[8:9]
	v_pk_mul_f32 v[12:13], v[26:27], v[0:1] op_sel_hi:[1,0]
	v_cvt_pk_bf16_f32 v11, v8, v9
	v_mov_b64_e32 v[8:9], v[106:107]
	s_nop 0
	v_mov_b64_e32 v[6:7], v[108:109]
	v_lshlrev_b32_e32 v2, 16, v7
	global_store_dwordx2 v[4:5], v[10:11], off offset:80
	v_lshlrev_b32_e32 v10, 16, v8
	v_mul_f32_e32 v1, 0xbfb8aa3b, v10
	v_exp_f32_e32 v1, v1
	v_and_b32_e32 v11, 0xffff0000, v8
	v_lshlrev_b32_e32 v8, 16, v9
	v_and_b32_e32 v9, 0xffff0000, v9
	v_add_f32_e32 v1, 1.0, v1
	v_rcp_f32_e32 v14, v1
	v_mul_f32_e32 v1, 0xbfb8aa3b, v11
	v_exp_f32_e32 v1, v1
	s_nop 0
	v_add_f32_e32 v1, 1.0, v1
	v_rcp_f32_e32 v15, v1
	s_nop 0
	v_pk_mul_f32 v[10:11], v[14:15], v[10:11]
	s_nop 0
	v_pk_mul_f32 v[10:11], v[12:13], v[10:11]
	v_pk_mul_f32 v[12:13], v[28:29], v[0:1] op_sel_hi:[1,0]
	v_mul_f32_e32 v1, 0xbfb8aa3b, v8
	v_exp_f32_e32 v1, v1
	v_cvt_pk_bf16_f32 v10, v10, v11
	v_add_f32_e32 v1, 1.0, v1
	v_rcp_f32_e32 v14, v1
	v_mul_f32_e32 v1, 0xbfb8aa3b, v9
	v_exp_f32_e32 v1, v1
	s_nop 0
	v_add_f32_e32 v1, 1.0, v1
	v_rcp_f32_e32 v15, v1
	v_and_b32_e32 v1, 0xffff0000, v7
	v_pk_mul_f32 v[8:9], v[14:15], v[8:9]
	s_nop 0
	v_pk_mul_f32 v[8:9], v[12:13], v[8:9]
	s_nop 0
	v_cvt_pk_bf16_f32 v11, v8, v9
	v_lshlrev_b32_e32 v8, 16, v6
	v_mul_f32_e32 v7, 0xbfb8aa3b, v8
	v_exp_f32_e32 v7, v7
	v_and_b32_e32 v9, 0xffff0000, v6
	global_store_dwordx2 v[4:5], v[10:11], off offset:96
	v_pk_mul_f32 v[10:11], v[30:31], v[0:1] op_sel_hi:[1,0]
	v_add_f32_e32 v7, 1.0, v7
	v_rcp_f32_e32 v12, v7
	v_mul_f32_e32 v7, 0xbfb8aa3b, v9
	v_exp_f32_e32 v7, v7
	v_mul_f32_e32 v6, v32, v0
	v_add_f32_e32 v7, 1.0, v7
	v_rcp_f32_e32 v13, v7
	v_mul_f32_e32 v7, 0xbfb8aa3b, v2
	v_exp_f32_e32 v7, v7
	v_pk_mul_f32 v[8:9], v[12:13], v[8:9]
	s_nop 0
	v_pk_mul_f32 v[8:9], v[10:11], v[8:9]
	v_add_f32_e32 v7, 1.0, v7
	v_rcp_f32_e32 v7, v7
	v_mov_b32_e32 v12, v33
	v_mul_f32_e32 v10, v7, v2
	v_mul_f32_e32 v2, 0xbfb8aa3b, v1
	v_exp_f32_e32 v2, v2
	s_nop 0
	v_add_f32_e32 v2, 1.0, v2
	v_rcp_f32_e32 v13, v2
	s_nop 0
	v_pk_mul_f32 v[0:1], v[12:13], v[0:1]
	s_nop 0
	v_mov_b32_e32 v7, v0
	v_mov_b32_e32 v11, v1
	v_cvt_pk_bf16_f32 v0, v8, v9
	v_pk_mul_f32 v[6:7], v[6:7], v[10:11]
	v_lshl_add_u64 v[8:9], v[4:5], 0, s[12:13]
	global_store_dword v[4:5], v0, off offset:112
	s_cbranch_execnz .LBB0_31
	s_branch .LBB0_46

; DI uint32_t pack2(float a, float b) { f2_t v = {a, b}; bf2_t r = __builtin_convertvector(v, bf2_t); return __builtin_bit_cast(uint32_t, r); }
; DI float bflo(uint32_t u) { return __uint_as_float(u << 16); }
; DI float bfhi(uint32_t u) { return __uint_as_float(u & 0xffff0000u); }
; DI float xsum32(float v) { unsigned u = __float_as_uint(v); auto r = __builtin_amdgcn_permlane32_swap(u, u, false, false); return __uint_as_float(r[0]) + __uint_as_float(r[1]); }
; DI float fsigmoid(float x) { return frcp(1.f + fexp2(-LOG2E * x)); }
; template <int MODE, bool FAST>
; DI void attn_item(const Params& p, int layer, int b, int hd, int qt, char* smem) {
;     ...
;   float inv = 1.f;
;   if (MODE != 0) { const float lt = xsum32(lrun); inv = 1.f / lt; }
;   const size_t tok = (size_t)(tokbase + tq);
;   const u16* zrow = PROJ + tok * LDP + O_ZA + MODE * 512 + hdl * 64;
;   u16* yrow = YBR + tok * LDY + MODE * 512 + hdl * 64;
; #pragma unroll
;   for (int dt = 0; dt < 2; ++dt)
; #pragma unroll
;     for (int g = 0; g < 4; ++g) {
;       const int d4 = dt * 32 + 8 * g + 4 * h;
;       uint2 zu = *(const uint2*)(zrow + d4);
;       float z0 = bflo(zu.x), z1 = bfhi(zu.x), z2 = bflo(zu.y), z3 = bfhi(zu.y);
;       float y0 = o[dt][4 * g] * inv, y1 = o[dt][4 * g + 1] * inv, y2 = o[dt][4 * g + 2] * inv, y3 = o[dt][4 * g + 3] * inv;
;       y0 *= z0 * fsigmoid(z0); y1 *= z1 * fsigmoid(z1); y2 *= z2 * fsigmoid(z2); y3 *= z3 * fsigmoid(z3);
;       *(uint2*)(yrow + d4) = make_uint2(pack2(y0, y1), pack2(y2, y3));
;     }
.LBB0_279:
	v_mov_b32_e32 v0, v113
	s_nop 1
	v_permlane32_swap_b32_e32 v113, v0
	v_add_f32_e32 v0, v113, v0
	v_div_scale_f32 v1, s[14:15], v0, v0, 1.0
	v_rcp_f32_e32 v2, v1
	s_lshl_b32 s16, s7, 7
	s_movk_i32 s6, 0xdd80
	v_mov_b32_e32 v51, v3
	v_fma_f32 v4, -v1, v2, 1.0
	v_fmac_f32_e32 v2, v4, v2
	v_div_scale_f32 v4, vcc, 1.0, v0, 1.0
	v_mul_f32_e32 v5, v4, v2
	v_fma_f32 v6, -v1, v5, v4
	v_fmac_f32_e32 v5, v6, v2
	v_fma_f32 v1, -v1, v5, v4
	v_div_fmas_f32 v1, v1, v2, v5
	v_div_fixup_f32 v0, v1, v0, 1.0
	v_lshl_add_u32 v1, s58, 12, v110
	v_mov_b64_e32 v[4:5], s[94:95]
	v_mad_i64_i32 v[4:5], s[14:15], v1, s54, v[4:5]
	v_lshl_add_u64 v[6:7], v[4:5], 0, s[16:17]
	v_mad_i64_i32 v[4:5], s[14:15], v1, s6, v[4:5]
	v_lshlrev_b64 v[8:9], 1, v[50:51]
	v_lshl_add_u64 v[10:11], v[6:7], 0, v[8:9]
	s_mov_b64 s[14:15], 0x4e98e80
	s_mov_b32 s6, 0x4e98000
	v_lshl_add_u64 v[6:7], v[10:11], 0, s[14:15]
	v_add_co_u32_e32 v10, vcc, s6, v10
	v_pk_mul_f32 v[14:15], v[34:35], v[0:1] op_sel_hi:[1,0]
	s_nop 0
	v_addc_co_u32_e32 v11, vcc, 0, v11, vcc
	global_load_dwordx2 v[10:11], v[10:11], off offset:3712
	global_load_dwordx2 v[96:97], v[6:7], off offset:16
	global_load_dwordx2 v[98:99], v[6:7], off offset:32
	global_load_dwordx2 v[100:101], v[6:7], off offset:48
	global_load_dwordx2 v[102:103], v[6:7], off offset:64
	global_load_dwordx2 v[104:105], v[6:7], off offset:80
	global_load_dwordx2 v[106:107], v[6:7], off offset:96
	global_load_dwordx2 v[108:109], v[6:7], off offset:112
	v_lshl_add_u64 v[4:5], v[4:5], 0, s[16:17]
	v_lshl_add_u64 v[8:9], v[4:5], 0, v[8:9]
	s_mov_b64 s[14:15], 0x15c98400
	v_lshl_add_u64 v[4:5], v[8:9], 0, s[14:15]
	v_add_co_u32_e32 v8, vcc, s3, v8
	s_mov_b64 s[14:15], 0x70
	s_nop 0
	v_addc_co_u32_e32 v9, vcc, 0, v9, vcc
	s_waitcnt vmcnt(0)
	v_lshlrev_b32_e32 v12, 16, v10
	v_mul_f32_e32 v1, 0xbfb8aa3b, v12
	v_exp_f32_e32 v1, v1
	v_and_b32_e32 v13, 0xffff0000, v10
	v_lshlrev_b32_e32 v10, 16, v11
	v_and_b32_e32 v11, 0xffff0000, v11
	v_add_f32_e32 v1, 1.0, v1
	v_rcp_f32_e32 v16, v1
	v_mul_f32_e32 v1, 0xbfb8aa3b, v13
	v_exp_f32_e32 v1, v1
	s_nop 0
	v_add_f32_e32 v1, 1.0, v1
	v_rcp_f32_e32 v17, v1
	s_nop 0
	v_pk_mul_f32 v[12:13], v[16:17], v[12:13]
	s_nop 0
	v_pk_mul_f32 v[12:13], v[14:15], v[12:13]
	v_pk_mul_f32 v[14:15], v[36:37], v[0:1] op_sel_hi:[1,0]
	v_mul_f32_e32 v1, 0xbfb8aa3b, v10
	v_exp_f32_e32 v1, v1
	v_cvt_pk_bf16_f32 v12, v12, v13
	v_add_f32_e32 v1, 1.0, v1
	v_rcp_f32_e32 v16, v1
	v_mul_f32_e32 v1, 0xbfb8aa3b, v11
	v_exp_f32_e32 v1, v1
	s_nop 0
	v_add_f32_e32 v1, 1.0, v1
	v_rcp_f32_e32 v17, v1
	s_nop 0
	v_pk_mul_f32 v[10:11], v[16:17], v[10:11]
	s_nop 0
	v_pk_mul_f32 v[10:11], v[14:15], v[10:11]
	s_nop 0
	v_cvt_pk_bf16_f32 v13, v10, v11
	global_store_dwordx2 v[8:9], v[12:13], off offset:1024
	v_mov_b64_e32 v[8:9], v[96:97]
	v_pk_mul_f32 v[12:13], v[38:39], v[0:1] op_sel_hi:[1,0]
	v_lshlrev_b32_e32 v10, 16, v8
	v_mul_f32_e32 v1, 0xbfb8aa3b, v10
	v_exp_f32_e32 v1, v1
	v_and_b32_e32 v11, 0xffff0000, v8
	v_lshlrev_b32_e32 v8, 16, v9
	v_and_b32_e32 v9, 0xffff0000, v9
	v_add_f32_e32 v1, 1.0, v1
	v_rcp_f32_e32 v14, v1
	v_mul_f32_e32 v1, 0xbfb8aa3b, v11
	v_exp_f32_e32 v1, v1
	s_nop 0
	v_add_f32_e32 v1, 1.0, v1
	v_rcp_f32_e32 v15, v1
	s_nop 0
	v_pk_mul_f32 v[10:11], v[14:15], v[10:11]
	s_nop 0
	v_pk_mul_f32 v[10:11], v[12:13], v[10:11]
	v_pk_mul_f32 v[12:13], v[40:41], v[0:1] op_sel_hi:[1,0]
	v_mul_f32_e32 v1, 0xbfb8aa3b, v8
	v_exp_f32_e32 v1, v1
	v_cvt_pk_bf16_f32 v10, v10, v11
	v_add_f32_e32 v1, 1.0, v1
	v_rcp_f32_e32 v14, v1
	v_mul_f32_e32 v1, 0xbfb8aa3b, v9
	v_exp_f32_e32 v1, v1
	s_nop 0
	v_add_f32_e32 v1, 1.0, v1
	v_rcp_f32_e32 v15, v1
	s_nop 0
	v_pk_mul_f32 v[8:9], v[14:15], v[8:9]
	s_nop 0
	v_pk_mul_f32 v[8:9], v[12:13], v[8:9]
	v_pk_mul_f32 v[12:13], v[42:43], v[0:1] op_sel_hi:[1,0]
	v_cvt_pk_bf16_f32 v11, v8, v9
	v_mov_b64_e32 v[8:9], v[98:99]
	s_nop 0
	global_store_dwordx2 v[4:5], v[10:11], off offset:16
	v_lshlrev_b32_e32 v10, 16, v8
	v_mul_f32_e32 v1, 0xbfb8aa3b, v10
	v_exp_f32_e32 v1, v1
	v_and_b32_e32 v11, 0xffff0000, v8
	v_lshlrev_b32_e32 v8, 16, v9
	v_and_b32_e32 v9, 0xffff0000, v9
	v_add_f32_e32 v1, 1.0, v1
	v_rcp_f32_e32 v14, v1
	v_mul_f32_e32 v1, 0xbfb8aa3b, v11
	v_exp_f32_e32 v1, v1
	s_nop 0
	v_add_f32_e32 v1, 1.0, v1
	v_rcp_f32_e32 v15, v1
	s_nop 0
	v_pk_mul_f32 v[10:11], v[14:15], v[10:11]
	s_nop 0
	v_pk_mul_f32 v[10:11], v[12:13], v[10:11]
	v_pk_mul_f32 v[12:13], v[44:45], v[0:1] op_sel_hi:[1,0]
	v_mul_f32_e32 v1, 0xbfb8aa3b, v8
	v_exp_f32_e32 v1, v1
	v_cvt_pk_bf16_f32 v10, v10, v11
	v_add_f32_e32 v1, 1.0, v1
	v_rcp_f32_e32 v14, v1
	v_mul_f32_e32 v1, 0xbfb8aa3b, v9
	v_exp_f32_e32 v1, v1
	s_nop 0
	v_add_f32_e32 v1, 1.0, v1
	v_rcp_f32_e32 v15, v1
	s_nop 0
	v_pk_mul_f32 v[8:9], v[14:15], v[8:9]
	s_nop 0
	v_pk_mul_f32 v[8:9], v[12:13], v[8:9]
	v_pk_mul_f32 v[12:13], v[46:47], v[0:1] op_sel_hi:[1,0]
	v_cvt_pk_bf16_f32 v11, v8, v9
	v_mov_b64_e32 v[8:9], v[100:101]
	s_nop 0
	global_store_dwordx2 v[4:5], v[10:11], off offset:32
	v_lshlrev_b32_e32 v10, 16, v8
	v_mul_f32_e32 v1, 0xbfb8aa3b, v10
	v_exp_f32_e32 v1, v1
	v_and_b32_e32 v11, 0xffff0000, v8
	v_lshlrev_b32_e32 v8, 16, v9
; DI uint32_t pack2(float a, float b) { f2_t v = {a, b}; bf2_t r = __builtin_convertvector(v, bf2_t); return __builtin_bit_cast(uint32_t, r); }
; DI float bflo(uint32_t u) { return __uint_as_float(u << 16); }
; DI float bfhi(uint32_t u) { return __uint_as_float(u & 0xffff0000u); }
; DI float fsigmoid(float x) { return frcp(1.f + fexp2(-LOG2E * x)); }
; template <int MODE, bool FAST>
; DI void attn_item(const Params& p, int layer, int b, int hd, int qt, char* smem) {
;     ...
;       const int d4 = dt * 32 + 8 * g + 4 * h;
;       uint2 zu = *(const uint2*)(zrow + d4);
;       float z0 = bflo(zu.x), z1 = bfhi(zu.x), z2 = bflo(zu.y), z3 = bfhi(zu.y);
;       float y0 = o[dt][4 * g] * inv, y1 = o[dt][4 * g + 1] * inv, y2 = o[dt][4 * g + 2] * inv, y3 = o[dt][4 * g + 3] * inv;
;       y0 *= z0 * fsigmoid(z0); y1 *= z1 * fsigmoid(z1); y2 *= z2 * fsigmoid(z2); y3 *= z3 * fsigmoid(z3);
;       *(uint2*)(yrow + d4) = make_uint2(pack2(y0, y1), pack2(y2, y3));
;     }
	v_and_b32_e32 v9, 0xffff0000, v9
	v_add_f32_e32 v1, 1.0, v1
	v_rcp_f32_e32 v14, v1
	v_mul_f32_e32 v1, 0xbfb8aa3b, v11
	v_exp_f32_e32 v1, v1
	s_nop 0
	v_add_f32_e32 v1, 1.0, v1
	v_rcp_f32_e32 v15, v1
	s_nop 0
	v_pk_mul_f32 v[10:11], v[14:15], v[10:11]
	s_nop 0
	v_pk_mul_f32 v[10:11], v[12:13], v[10:11]
	v_pk_mul_f32 v[12:13], v[48:49], v[0:1] op_sel_hi:[1,0]
	v_mul_f32_e32 v1, 0xbfb8aa3b, v8
	v_exp_f32_e32 v1, v1
	v_cvt_pk_bf16_f32 v10, v10, v11
	v_add_f32_e32 v1, 1.0, v1
	v_rcp_f32_e32 v14, v1
	v_mul_f32_e32 v1, 0xbfb8aa3b, v9
	v_exp_f32_e32 v1, v1
	s_nop 0
	v_add_f32_e32 v1, 1.0, v1
	v_rcp_f32_e32 v15, v1
	s_nop 0
	v_pk_mul_f32 v[8:9], v[14:15], v[8:9]
	s_nop 0
	v_pk_mul_f32 v[8:9], v[12:13], v[8:9]
	v_pk_mul_f32 v[12:13], v[18:19], v[0:1] op_sel_hi:[1,0]
	v_cvt_pk_bf16_f32 v11, v8, v9
	v_mov_b64_e32 v[8:9], v[102:103]
	s_nop 0
	global_store_dwordx2 v[4:5], v[10:11], off offset:48
	v_lshlrev_b32_e32 v10, 16, v8
	v_mul_f32_e32 v1, 0xbfb8aa3b, v10
	v_exp_f32_e32 v1, v1
	v_and_b32_e32 v11, 0xffff0000, v8
	v_lshlrev_b32_e32 v8, 16, v9
	v_and_b32_e32 v9, 0xffff0000, v9
	v_add_f32_e32 v1, 1.0, v1
	v_rcp_f32_e32 v14, v1
	v_mul_f32_e32 v1, 0xbfb8aa3b, v11
	v_exp_f32_e32 v1, v1
	s_nop 0
	v_add_f32_e32 v1, 1.0, v1
	v_rcp_f32_e32 v15, v1
	s_nop 0
	v_pk_mul_f32 v[10:11], v[14:15], v[10:11]
	s_nop 0
	v_pk_mul_f32 v[10:11], v[12:13], v[10:11]
	v_pk_mul_f32 v[12:13], v[20:21], v[0:1] op_sel_hi:[1,0]
	v_mul_f32_e32 v1, 0xbfb8aa3b, v8
	v_exp_f32_e32 v1, v1
	v_cvt_pk_bf16_f32 v10, v10, v11
	v_add_f32_e32 v1, 1.0, v1
	v_rcp_f32_e32 v14, v1
	v_mul_f32_e32 v1, 0xbfb8aa3b, v9
	v_exp_f32_e32 v1, v1
	s_nop 0
	v_add_f32_e32 v1, 1.0, v1
	v_rcp_f32_e32 v15, v1
	s_nop 0
	v_pk_mul_f32 v[8:9], v[14:15], v[8:9]
	s_nop 0
	v_pk_mul_f32 v[8:9], v[12:13], v[8:9]
	v_pk_mul_f32 v[12:13], v[22:23], v[0:1] op_sel_hi:[1,0]
	v_cvt_pk_bf16_f32 v11, v8, v9
	v_mov_b64_e32 v[8:9], v[104:105]
	s_nop 0
	global_store_dwordx2 v[4:5], v[10:11], off offset:64
	v_lshlrev_b32_e32 v10, 16, v8
	v_mul_f32_e32 v1, 0xbfb8aa3b, v10
	v_exp_f32_e32 v1, v1
	v_and_b32_e32 v11, 0xffff0000, v8
	v_lshlrev_b32_e32 v8, 16, v9
	v_and_b32_e32 v9, 0xffff0000, v9
	v_add_f32_e32 v1, 1.0, v1
	v_rcp_f32_e32 v14, v1
	v_mul_f32_e32 v1, 0xbfb8aa3b, v11
	v_exp_f32_e32 v1, v1
	s_nop 0
	v_add_f32_e32 v1, 1.0, v1
	v_rcp_f32_e32 v15, v1
	s_nop 0
	v_pk_mul_f32 v[10:11], v[14:15], v[10:11]
	s_nop 0
	v_pk_mul_f32 v[10:11], v[12:13], v[10:11]
	v_pk_mul_f32 v[12:13], v[24:25], v[0:1] op_sel_hi:[1,0]
	v_mul_f32_e32 v1, 0xbfb8aa3b, v8
	v_exp_f32_e32 v1, v1
	v_cvt_pk_bf16_f32 v10, v10, v11
	v_add_f32_e32 v1, 1.0, v1
	v_rcp_f32_e32 v14, v1
	v_mul_f32_e32 v1, 0xbfb8aa3b, v9
	v_exp_f32_e32 v1, v1
	s_nop 0
	v_add_f32_e32 v1, 1.0, v1
	v_rcp_f32_e32 v15, v1
	s_nop 0
	v_pk_mul_f32 v[8:9], v[14:15], v[8:9]
	s_nop 0
	v_pk_mul_f32 v[8:9], v[12:13], v[8:9]
	v_pk_mul_f32 v[12:13], v[26:27], v[0:1] op_sel_hi:[1,0]
	v_cvt_pk_bf16_f32 v11, v8, v9
	v_mov_b64_e32 v[8:9], v[106:107]
	s_nop 0
	v_mov_b64_e32 v[6:7], v[108:109]
	v_lshlrev_b32_e32 v2, 16, v7
	global_store_dwordx2 v[4:5], v[10:11], off offset:80
	v_lshlrev_b32_e32 v10, 16, v8
	v_mul_f32_e32 v1, 0xbfb8aa3b, v10
	v_exp_f32_e32 v1, v1
	v_and_b32_e32 v11, 0xffff0000, v8
	v_lshlrev_b32_e32 v8, 16, v9
	v_and_b32_e32 v9, 0xffff0000, v9
	v_add_f32_e32 v1, 1.0, v1
	v_rcp_f32_e32 v14, v1
	v_mul_f32_e32 v1, 0xbfb8aa3b, v11
	v_exp_f32_e32 v1, v1
	s_nop 0
	v_add_f32_e32 v1, 1.0, v1
	v_rcp_f32_e32 v15, v1
	s_nop 0
	v_pk_mul_f32 v[10:11], v[14:15], v[10:11]
	s_nop 0
	v_pk_mul_f32 v[10:11], v[12:13], v[10:11]
	v_pk_mul_f32 v[12:13], v[28:29], v[0:1] op_sel_hi:[1,0]
	v_mul_f32_e32 v1, 0xbfb8aa3b, v8
	v_exp_f32_e32 v1, v1
	v_cvt_pk_bf16_f32 v10, v10, v11
	v_add_f32_e32 v1, 1.0, v1
	v_rcp_f32_e32 v14, v1
	v_mul_f32_e32 v1, 0xbfb8aa3b, v9
	v_exp_f32_e32 v1, v1
	s_nop 0
	v_add_f32_e32 v1, 1.0, v1
	v_rcp_f32_e32 v15, v1
	v_and_b32_e32 v1, 0xffff0000, v7
	v_pk_mul_f32 v[8:9], v[14:15], v[8:9]
	s_nop 0
	v_pk_mul_f32 v[8:9], v[12:13], v[8:9]
	s_nop 0
	v_cvt_pk_bf16_f32 v11, v8, v9
	v_lshlrev_b32_e32 v8, 16, v6
	v_mul_f32_e32 v7, 0xbfb8aa3b, v8
	v_exp_f32_e32 v7, v7
	v_and_b32_e32 v9, 0xffff0000, v6
	global_store_dwordx2 v[4:5], v[10:11], off offset:96
	v_pk_mul_f32 v[10:11], v[30:31], v[0:1] op_sel_hi:[1,0]
	v_add_f32_e32 v7, 1.0, v7
	v_rcp_f32_e32 v12, v7
	v_mul_f32_e32 v7, 0xbfb8aa3b, v9
	v_exp_f32_e32 v7, v7
	v_mul_f32_e32 v6, v32, v0
	v_add_f32_e32 v7, 1.0, v7
	v_rcp_f32_e32 v13, v7
	v_mul_f32_e32 v7, 0xbfb8aa3b, v2
	v_exp_f32_e32 v7, v7
	v_pk_mul_f32 v[8:9], v[12:13], v[8:9]
	s_nop 0
	v_pk_mul_f32 v[8:9], v[10:11], v[8:9]
	v_add_f32_e32 v7, 1.0, v7
	v_rcp_f32_e32 v7, v7
	v_mov_b32_e32 v12, v33
	v_mul_f32_e32 v10, v7, v2
	v_mul_f32_e32 v2, 0xbfb8aa3b, v1
	v_exp_f32_e32 v2, v2
	s_nop 0
	v_add_f32_e32 v2, 1.0, v2
	v_rcp_f32_e32 v13, v2
	s_nop 0
	v_pk_mul_f32 v[0:1], v[12:13], v[0:1]
	s_nop 0
	v_mov_b32_e32 v7, v0
	v_mov_b32_e32 v11, v1
	v_cvt_pk_bf16_f32 v0, v8, v9
	v_pk_mul_f32 v[6:7], v[6:7], v[10:11]
	v_lshl_add_u64 v[8:9], v[4:5], 0, s[14:15]
	global_store_dword v[4:5], v0, off offset:112
	s_mov_b64 s[14:15], 0
	s_branch .LBB0_44
